# ada_item loop (phase-6 tail copy): vmcnt(0) after issuing the 8 weight loads relaxed to the counted vmcnt(7); later counted waits were already present
# speedup vs baseline: 1.0037x; 1.0012x over previous
.LBB0_210:
	global_load_dwordx4 v[62:65], v[56:57], off
	v_add_co_u32_e32 v36, vcc, s13, v56
	s_add_i32 s4, s4, 8
	s_nop 0
	v_addc_co_u32_e32 v37, vcc, 0, v57, vcc
	global_load_dwordx4 v[66:69], v[36:37], off
	v_add_co_u32_e32 v36, vcc, s12, v56
	s_cmpk_gt_u32 s4, 0x77
	s_nop 0
	v_addc_co_u32_e32 v37, vcc, 0, v57, vcc
	global_load_dwordx4 v[70:73], v[36:37], off
	v_add_co_u32_e32 v36, vcc, s5, v56
	s_nop 1
	v_addc_co_u32_e32 v37, vcc, 0, v57, vcc
	global_load_dwordx4 v[74:77], v[36:37], off
	v_add_co_u32_e32 v36, vcc, s25, v56
	s_nop 1
	v_addc_co_u32_e32 v37, vcc, 0, v57, vcc
	global_load_dwordx4 v[48:51], v[36:37], off
	v_add_co_u32_e32 v36, vcc, s26, v56
	s_nop 1
	v_addc_co_u32_e32 v37, vcc, 0, v57, vcc
	global_load_dwordx4 v[44:47], v[36:37], off
	v_add_co_u32_e32 v36, vcc, s27, v56
	s_nop 1
	v_addc_co_u32_e32 v37, vcc, 0, v57, vcc
	global_load_dwordx4 v[40:43], v[36:37], off
	v_add_co_u32_e32 v36, vcc, s28, v56
	s_nop 1
	v_addc_co_u32_e32 v37, vcc, 0, v57, vcc
	global_load_dwordx4 v[36:39], v[36:37], off
	ds_read_b128 v[78:81], v61
	ds_read_b128 v[52:55], v61 offset:16
	v_lshl_add_u64 v[56:57], v[56:57], 0, s[30:31]
	ds_read_b128 v[90:93], v61 offset:32768
	ds_read_b128 v[82:85], v61 offset:24576
	ds_read_b128 v[86:89], v61 offset:28672
	s_waitcnt vmcnt(7) lgkmcnt(0)
	v_pk_fma_f32 v[94:95], v[64:65], v[78:79], v[6:7] op_sel_hi:[1,0,1]
	v_pk_fma_f32 v[96:97], v[62:63], v[78:79], v[4:5] op_sel_hi:[1,0,1]
	ds_read_b128 v[4:7], v61 offset:4096
	s_waitcnt lgkmcnt(2)
	v_pk_fma_f32 v[26:27], v[64:65], v[82:83], v[26:27] op_sel_hi:[1,0,1]
	v_pk_fma_f32 v[24:25], v[62:63], v[82:83], v[24:25] op_sel_hi:[1,0,1]
	v_pk_fma_f32 v[34:35], v[64:65], v[90:91], v[34:35] op_sel_hi:[1,0,1]
	v_pk_fma_f32 v[32:33], v[62:63], v[90:91], v[32:33] op_sel_hi:[1,0,1]
	s_waitcnt lgkmcnt(0)
	v_pk_fma_f32 v[98:99], v[64:65], v[4:5], v[2:3] op_sel_hi:[1,0,1]
	v_pk_fma_f32 v[100:101], v[62:63], v[4:5], v[0:1] op_sel_hi:[1,0,1]
	ds_read_b128 v[0:3], v61 offset:8192
	s_waitcnt vmcnt(6)
	v_pk_fma_f32 v[32:33], v[66:67], v[90:91], v[32:33] op_sel:[0,1,0]
	v_pk_fma_f32 v[24:25], v[66:67], v[82:83], v[24:25] op_sel:[0,1,0]
	v_pk_fma_f32 v[30:31], v[64:65], v[86:87], v[30:31] op_sel_hi:[1,0,1]
	v_pk_fma_f32 v[28:29], v[62:63], v[86:87], v[28:29] op_sel_hi:[1,0,1]
	s_waitcnt lgkmcnt(0)
	v_pk_fma_f32 v[102:103], v[64:65], v[0:1], v[10:11] op_sel_hi:[1,0,1]
	v_pk_fma_f32 v[104:105], v[62:63], v[0:1], v[8:9] op_sel_hi:[1,0,1]
	ds_read_b128 v[8:11], v61 offset:12288
	v_pk_fma_f32 v[28:29], v[66:67], v[86:87], v[28:29] op_sel:[0,1,0]
	s_waitcnt lgkmcnt(0)
	v_pk_fma_f32 v[106:107], v[64:65], v[8:9], v[14:15] op_sel_hi:[1,0,1]
	v_pk_fma_f32 v[108:109], v[62:63], v[8:9], v[12:13] op_sel_hi:[1,0,1]
	ds_read_b128 v[12:15], v61 offset:16384
	s_waitcnt lgkmcnt(0)
	v_pk_fma_f32 v[110:111], v[64:65], v[12:13], v[18:19] op_sel_hi:[1,0,1]
	v_pk_fma_f32 v[112:113], v[62:63], v[12:13], v[16:17] op_sel_hi:[1,0,1]
	ds_read_b128 v[16:19], v61 offset:20480
	s_waitcnt lgkmcnt(0)
	v_pk_fma_f32 v[22:23], v[64:65], v[16:17], v[22:23] op_sel_hi:[1,0,1]
	v_pk_fma_f32 v[20:21], v[62:63], v[16:17], v[20:21] op_sel_hi:[1,0,1]
	v_pk_fma_f32 v[62:63], v[68:69], v[78:79], v[94:95] op_sel:[0,1,0]
	v_pk_fma_f32 v[64:65], v[66:67], v[78:79], v[96:97] op_sel:[0,1,0]
	v_pk_fma_f32 v[94:95], v[68:69], v[0:1], v[102:103] op_sel:[0,1,0]
	v_pk_fma_f32 v[0:1], v[66:67], v[0:1], v[104:105] op_sel:[0,1,0]
	v_pk_fma_f32 v[78:79], v[68:69], v[4:5], v[98:99] op_sel:[0,1,0]
	v_pk_fma_f32 v[4:5], v[66:67], v[4:5], v[100:101] op_sel:[0,1,0]
	v_pk_fma_f32 v[96:97], v[68:69], v[8:9], v[106:107] op_sel:[0,1,0]
	v_pk_fma_f32 v[8:9], v[66:67], v[8:9], v[108:109] op_sel:[0,1,0]
	v_pk_fma_f32 v[98:99], v[68:69], v[12:13], v[110:111] op_sel:[0,1,0]
	v_pk_fma_f32 v[12:13], v[66:67], v[12:13], v[112:113] op_sel:[0,1,0]
	v_pk_fma_f32 v[22:23], v[68:69], v[16:17], v[22:23] op_sel:[0,1,0]
	v_pk_fma_f32 v[16:17], v[66:67], v[16:17], v[20:21] op_sel:[0,1,0]
	v_pk_fma_f32 v[20:21], v[68:69], v[82:83], v[26:27] op_sel:[0,1,0]
	v_pk_fma_f32 v[26:27], v[68:69], v[86:87], v[30:31] op_sel:[0,1,0]
	v_pk_fma_f32 v[30:31], v[68:69], v[90:91], v[34:35] op_sel:[0,1,0]
	s_waitcnt vmcnt(5)
	v_pk_fma_f32 v[34:35], v[72:73], v[80:81], v[62:63] op_sel_hi:[1,0,1]
	v_pk_fma_f32 v[62:63], v[70:71], v[80:81], v[64:65] op_sel_hi:[1,0,1]
	v_pk_fma_f32 v[66:67], v[72:73], v[2:3], v[94:95] op_sel_hi:[1,0,1]
	v_pk_fma_f32 v[0:1], v[70:71], v[2:3], v[0:1] op_sel_hi:[1,0,1]
	v_mov_b32_e32 v2, v81
	v_pk_fma_f32 v[64:65], v[72:73], v[6:7], v[78:79] op_sel_hi:[1,0,1]
	v_pk_fma_f32 v[4:5], v[70:71], v[6:7], v[4:5] op_sel_hi:[1,0,1]
	s_waitcnt vmcnt(4)
	v_pk_fma_f32 v[80:81], v[76:77], v[2:3], v[34:35] op_sel_hi:[1,0,1]
	v_pk_fma_f32 v[62:63], v[74:75], v[2:3], v[62:63] op_sel_hi:[1,0,1]
	v_mov_b32_e32 v2, v7
	v_pk_fma_f32 v[8:9], v[70:71], v[10:11], v[8:9] op_sel_hi:[1,0,1]
	v_pk_fma_f32 v[78:79], v[72:73], v[14:15], v[98:99] op_sel_hi:[1,0,1]
	v_pk_fma_f32 v[12:13], v[70:71], v[14:15], v[12:13] op_sel_hi:[1,0,1]
	v_pk_fma_f32 v[86:87], v[70:71], v[18:19], v[16:17] op_sel_hi:[1,0,1]
	v_pk_fma_f32 v[94:95], v[70:71], v[84:85], v[24:25] op_sel_hi:[1,0,1]
	v_pk_fma_f32 v[98:99], v[70:71], v[88:89], v[28:29] op_sel_hi:[1,0,1]
	v_pk_fma_f32 v[70:71], v[70:71], v[92:93], v[32:33] op_sel_hi:[1,0,1]
	v_pk_fma_f32 v[32:33], v[76:77], v[2:3], v[64:65] op_sel_hi:[1,0,1]
	v_pk_fma_f32 v[34:35], v[74:75], v[2:3], v[4:5] op_sel_hi:[1,0,1]
	v_mov_b32_e32 v2, v3
	v_pk_fma_f32 v[68:69], v[72:73], v[10:11], v[96:97] op_sel_hi:[1,0,1]
	v_pk_fma_f32 v[82:83], v[72:73], v[18:19], v[22:23] op_sel_hi:[1,0,1]
	v_pk_fma_f32 v[90:91], v[72:73], v[84:85], v[20:21] op_sel_hi:[1,0,1]
	v_pk_fma_f32 v[96:97], v[72:73], v[88:89], v[26:27] op_sel_hi:[1,0,1]
	v_pk_fma_f32 v[72:73], v[72:73], v[92:93], v[30:31] op_sel_hi:[1,0,1]
	v_pk_fma_f32 v[30:31], v[74:75], v[2:3], v[0:1] op_sel_hi:[1,0,1]
	v_mov_b32_e32 v0, v11
	s_waitcnt vmcnt(3)
	v_pk_fma_f32 v[6:7], v[48:49], v[52:53], v[62:63] op_sel_hi:[1,0,1]
	ds_read_b128 v[62:65], v61 offset:4112
	v_pk_fma_f32 v[24:25], v[76:77], v[0:1], v[68:69] op_sel_hi:[1,0,1]
	v_pk_fma_f32 v[26:27], v[74:75], v[0:1], v[8:9] op_sel_hi:[1,0,1]
	v_mov_b32_e32 v0, v15
	v_pk_fma_f32 v[20:21], v[76:77], v[0:1], v[78:79] op_sel_hi:[1,0,1]
	v_pk_fma_f32 v[22:23], v[74:75], v[0:1], v[12:13] op_sel_hi:[1,0,1]
	v_mov_b32_e32 v0, v19
	v_pk_fma_f32 v[16:17], v[76:77], v[0:1], v[82:83] op_sel_hi:[1,0,1]
	v_pk_fma_f32 v[18:19], v[74:75], v[0:1], v[86:87] op_sel_hi:[1,0,1]
	v_mov_b32_e32 v0, v85
	v_pk_fma_f32 v[28:29], v[76:77], v[2:3], v[66:67] op_sel_hi:[1,0,1]
	v_pk_fma_f32 v[12:13], v[76:77], v[0:1], v[90:91] op_sel_hi:[1,0,1]
	v_pk_fma_f32 v[14:15], v[74:75], v[0:1], v[94:95] op_sel_hi:[1,0,1]
	v_mov_b32_e32 v0, v89
	v_mov_b32_e32 v2, v93
	v_pk_fma_f32 v[8:9], v[76:77], v[0:1], v[96:97] op_sel_hi:[1,0,1]
	v_pk_fma_f32 v[10:11], v[74:75], v[0:1], v[98:99] op_sel_hi:[1,0,1]
	v_pk_fma_f32 v[0:1], v[76:77], v[2:3], v[72:73] op_sel_hi:[1,0,1]
	v_pk_fma_f32 v[2:3], v[74:75], v[2:3], v[70:71] op_sel_hi:[1,0,1]
	v_pk_fma_f32 v[4:5], v[50:51], v[52:53], v[80:81] op_sel_hi:[1,0,1]
	ds_read_b128 v[74:77], v61 offset:32784
	s_waitcnt lgkmcnt(1)
	v_pk_fma_f32 v[78:79], v[50:51], v[62:63], v[32:33] op_sel_hi:[1,0,1]
	v_pk_fma_f32 v[80:81], v[48:49], v[62:63], v[34:35] op_sel_hi:[1,0,1]
	ds_read_b128 v[32:35], v61 offset:8208
	ds_read_b128 v[66:69], v61 offset:24592
	ds_read_b128 v[70:73], v61 offset:28688
	s_waitcnt lgkmcnt(3)
	v_pk_fma_f32 v[0:1], v[50:51], v[74:75], v[0:1] op_sel_hi:[1,0,1]
	v_pk_fma_f32 v[2:3], v[48:49], v[74:75], v[2:3] op_sel_hi:[1,0,1]
	s_waitcnt lgkmcnt(2)
	v_pk_fma_f32 v[82:83], v[50:51], v[32:33], v[28:29] op_sel_hi:[1,0,1]
	v_pk_fma_f32 v[84:85], v[48:49], v[32:33], v[30:31] op_sel_hi:[1,0,1]
	ds_read_b128 v[28:31], v61 offset:12304
	s_waitcnt lgkmcnt(2)
	v_pk_fma_f32 v[12:13], v[50:51], v[66:67], v[12:13] op_sel_hi:[1,0,1]
	s_waitcnt lgkmcnt(1)
	v_pk_fma_f32 v[8:9], v[50:51], v[70:71], v[8:9] op_sel_hi:[1,0,1]
	v_pk_fma_f32 v[14:15], v[48:49], v[66:67], v[14:15] op_sel_hi:[1,0,1]
	v_pk_fma_f32 v[10:11], v[48:49], v[70:71], v[10:11] op_sel_hi:[1,0,1]
	s_waitcnt lgkmcnt(0)
	v_pk_fma_f32 v[86:87], v[50:51], v[28:29], v[24:25] op_sel_hi:[1,0,1]
	v_pk_fma_f32 v[88:89], v[48:49], v[28:29], v[26:27] op_sel_hi:[1,0,1]
	ds_read_b128 v[24:27], v61 offset:16400
	s_waitcnt vmcnt(2)
	v_pk_fma_f32 v[4:5], v[46:47], v[52:53], v[4:5] op_sel:[0,1,0]
	v_pk_fma_f32 v[6:7], v[44:45], v[52:53], v[6:7] op_sel:[0,1,0]
	v_pk_fma_f32 v[52:53], v[46:47], v[32:33], v[82:83] op_sel:[0,1,0]
	v_pk_fma_f32 v[32:33], v[44:45], v[32:33], v[84:85] op_sel:[0,1,0]
	s_waitcnt lgkmcnt(0)
	v_pk_fma_f32 v[90:91], v[50:51], v[24:25], v[20:21] op_sel_hi:[1,0,1]
	v_pk_fma_f32 v[92:93], v[48:49], v[24:25], v[22:23] op_sel_hi:[1,0,1]
	ds_read_b128 v[20:23], v61 offset:20496
	v_pk_fma_f32 v[12:13], v[46:47], v[66:67], v[12:13] op_sel:[0,1,0]
	v_pk_fma_f32 v[8:9], v[46:47], v[70:71], v[8:9] op_sel:[0,1,0]
	v_pk_fma_f32 v[0:1], v[46:47], v[74:75], v[0:1] op_sel:[0,1,0]
	v_pk_fma_f32 v[14:15], v[44:45], v[66:67], v[14:15] op_sel:[0,1,0]
	s_waitcnt lgkmcnt(0)
	v_pk_fma_f32 v[16:17], v[50:51], v[20:21], v[16:17] op_sel_hi:[1,0,1]
	v_pk_fma_f32 v[18:19], v[48:49], v[20:21], v[18:19] op_sel_hi:[1,0,1]
	v_pk_fma_f32 v[48:49], v[46:47], v[62:63], v[78:79] op_sel:[0,1,0]
	v_pk_fma_f32 v[50:51], v[44:45], v[62:63], v[80:81] op_sel:[0,1,0]
	v_pk_fma_f32 v[62:63], v[46:47], v[28:29], v[86:87] op_sel:[0,1,0]
	v_pk_fma_f32 v[28:29], v[44:45], v[28:29], v[88:89] op_sel:[0,1,0]
	v_pk_fma_f32 v[78:79], v[46:47], v[24:25], v[90:91] op_sel:[0,1,0]
	v_pk_fma_f32 v[24:25], v[44:45], v[24:25], v[92:93] op_sel:[0,1,0]
	v_pk_fma_f32 v[16:17], v[46:47], v[20:21], v[16:17] op_sel:[0,1,0]
	v_pk_fma_f32 v[18:19], v[44:45], v[20:21], v[18:19] op_sel:[0,1,0]
	v_pk_fma_f32 v[10:11], v[44:45], v[70:71], v[10:11] op_sel:[0,1,0]
	v_pk_fma_f32 v[2:3], v[44:45], v[74:75], v[2:3] op_sel:[0,1,0]
	s_waitcnt vmcnt(1)
	v_pk_fma_f32 v[4:5], v[42:43], v[54:55], v[4:5] op_sel_hi:[1,0,1]
	v_pk_fma_f32 v[20:21], v[40:41], v[54:55], v[6:7] op_sel_hi:[1,0,1]
	v_pk_fma_f32 v[44:45], v[42:43], v[64:65], v[48:49] op_sel_hi:[1,0,1]
	v_pk_fma_f32 v[46:47], v[40:41], v[64:65], v[50:51] op_sel_hi:[1,0,1]
	v_pk_fma_f32 v[48:49], v[42:43], v[34:35], v[52:53] op_sel_hi:[1,0,1]
	v_pk_fma_f32 v[32:33], v[40:41], v[34:35], v[32:33] op_sel_hi:[1,0,1]
	v_pk_fma_f32 v[50:51], v[42:43], v[30:31], v[62:63] op_sel_hi:[1,0,1]
	v_pk_fma_f32 v[28:29], v[40:41], v[30:31], v[28:29] op_sel_hi:[1,0,1]
	v_pk_fma_f32 v[52:53], v[42:43], v[26:27], v[78:79] op_sel_hi:[1,0,1]
	v_pk_fma_f32 v[24:25], v[40:41], v[26:27], v[24:25] op_sel_hi:[1,0,1]
	v_pk_fma_f32 v[62:63], v[42:43], v[22:23], v[16:17] op_sel_hi:[1,0,1]
	v_pk_fma_f32 v[70:71], v[42:43], v[68:69], v[12:13] op_sel_hi:[1,0,1]
	v_pk_fma_f32 v[78:79], v[42:43], v[72:73], v[8:9] op_sel_hi:[1,0,1]
	v_pk_fma_f32 v[42:43], v[42:43], v[76:77], v[0:1] op_sel_hi:[1,0,1]
	v_mov_b32_e32 v0, v55
	v_mov_b32_e32 v8, v35
	v_mov_b32_e32 v12, v31
	v_mov_b32_e32 v16, v27
	v_pk_fma_f32 v[66:67], v[40:41], v[22:23], v[18:19] op_sel_hi:[1,0,1]
	v_pk_fma_f32 v[74:75], v[40:41], v[68:69], v[14:15] op_sel_hi:[1,0,1]
	v_pk_fma_f32 v[80:81], v[40:41], v[72:73], v[10:11] op_sel_hi:[1,0,1]
	v_pk_fma_f32 v[40:41], v[40:41], v[76:77], v[2:3] op_sel_hi:[1,0,1]
	s_waitcnt vmcnt(0)
	v_pk_fma_f32 v[6:7], v[38:39], v[0:1], v[4:5] op_sel_hi:[1,0,1]
	v_pk_fma_f32 v[4:5], v[36:37], v[0:1], v[20:21] op_sel_hi:[1,0,1]
	v_mov_b32_e32 v0, v65
	v_pk_fma_f32 v[10:11], v[38:39], v[8:9], v[48:49] op_sel_hi:[1,0,1]
	v_pk_fma_f32 v[8:9], v[36:37], v[8:9], v[32:33] op_sel_hi:[1,0,1]
	v_pk_fma_f32 v[14:15], v[38:39], v[12:13], v[50:51] op_sel_hi:[1,0,1]
	v_pk_fma_f32 v[12:13], v[36:37], v[12:13], v[28:29] op_sel_hi:[1,0,1]
	v_pk_fma_f32 v[18:19], v[38:39], v[16:17], v[52:53] op_sel_hi:[1,0,1]
	v_pk_fma_f32 v[16:17], v[36:37], v[16:17], v[24:25] op_sel_hi:[1,0,1]
	v_mov_b32_e32 v20, v23
	v_mov_b32_e32 v24, v69
	v_mov_b32_e32 v28, v73
	v_mov_b32_e32 v32, v77
	v_pk_fma_f32 v[2:3], v[38:39], v[0:1], v[44:45] op_sel_hi:[1,0,1]
	v_pk_fma_f32 v[0:1], v[36:37], v[0:1], v[46:47] op_sel_hi:[1,0,1]
	v_pk_fma_f32 v[22:23], v[38:39], v[20:21], v[62:63] op_sel_hi:[1,0,1]
	v_pk_fma_f32 v[20:21], v[36:37], v[20:21], v[66:67] op_sel_hi:[1,0,1]
	v_pk_fma_f32 v[26:27], v[38:39], v[24:25], v[70:71] op_sel_hi:[1,0,1]
	v_pk_fma_f32 v[24:25], v[36:37], v[24:25], v[74:75] op_sel_hi:[1,0,1]
	v_pk_fma_f32 v[30:31], v[38:39], v[28:29], v[78:79] op_sel_hi:[1,0,1]
	v_pk_fma_f32 v[28:29], v[36:37], v[28:29], v[80:81] op_sel_hi:[1,0,1]
	v_pk_fma_f32 v[34:35], v[38:39], v[32:33], v[42:43] op_sel_hi:[1,0,1]
	v_pk_fma_f32 v[32:33], v[36:37], v[32:33], v[40:41] op_sel_hi:[1,0,1]
	v_add_u32_e32 v61, 32, v61
	s_cbranch_scc0 .LBB0_210
	v_and_b32_e32 v36, 0xfc, v59
	s_movk_i32 s4, 0x2400
	v_lshlrev_b32_e32 v36, 2, v36
	v_mul_lo_u32 v37, v60, s4
	s_movk_i32 s4, 0x900
	v_add3_u32 v36, 0, v36, v37
	v_cmp_gt_i32_e32 vcc, s4, v58
	ds_write_b128 v36, v[4:7] offset:36864
	ds_write_b128 v36, v[0:3] offset:37888
	ds_write_b128 v36, v[8:11] offset:38912
	ds_write_b128 v36, v[12:15] offset:39936
	ds_write_b128 v36, v[16:19] offset:40960
	ds_write_b128 v36, v[20:23] offset:41984
	ds_write_b128 v36, v[24:27] offset:43008
	ds_write_b128 v36, v[28:31] offset:44032
	ds_write_b128 v36, v[32:35] offset:45056
	s_waitcnt lgkmcnt(0)
	s_barrier
	s_and_saveexec_b64 s[4:5], vcc
	v_readlane_b32 s8, v255, 40
	v_readlane_b32 s9, v255, 41
	s_cbranch_execz .LBB0_216
	s_load_dwordx16 s[48:63], s[8:9], 0x50
	v_and_b32_e32 v0, 0xff, v58
	v_readlane_b32 s6, v253, 35
	v_lshl_add_u32 v4, v0, 2, 0
	s_nop 0
	v_or_b32_e32 v0, s6, v0
	v_lshlrev_b32_e32 v176, 2, v0
	s_waitcnt lgkmcnt(0)
	v_lshl_add_u64 v[0:1], s[50:51], 0, v[176:177]
	s_mov_b64 s[6:7], 0xc000
	v_lshl_add_u64 v[0:1], v[0:1], 0, s[6:7]
	s_load_dwordx2 s[6:7], s[8:9], 0xe0
	s_waitcnt lgkmcnt(0)
	v_lshl_add_u64 v[2:3], s[6:7], 0, v[176:177]
	s_mov_b64 s[6:7], 0
	s_branch .LBB0_214
